# filter producer: chain of row block it+1 issued under the epilogue of row block it, packed f32 epilogue, kernarg pointers from live SGPRs
# baseline (speedup 1.0000x reference)
.LBB0_224:
	s_waitcnt vmcnt(0)
	v_readlane_b32 s0, v240, 22
	v_readlane_b32 s1, v240, 23
	s_barrier
	v_and_b32_e32 v2, 63, v1
	v_and_b32_e32 v3, 31, v2
	v_lshrrev_b32_e32 v4, 5, v2
	v_lshrrev_b32_e32 v6, 6, v1
	v_mov_b32_e32 v82, 0
	s_mov_b32 s61, 0x447fc000
	v_lshlrev_b32_e32 v81, 7, v3
	v_readfirstlane_b32 s92, v6
	v_lshl_add_u32 v81, v4, 4, v81
	v_cmp_eq_u32_e64 s[14:15], 1, v4
	v_mov_b32_e32 v8, 0x3d4ccccd
	v_mov_b32_e32 v9, 0x3d4ccccd
	s_mov_b32 s93, s2
.Lpf_item:
	s_cmpk_gt_u32 s93, 0xff
	s_cbranch_scc1 .Lpf_end
	s_lshr_b32 s94, s93, 5
	s_lshl_b32 s94, s94, 3
	s_add_i32 s94, s94, s92
	s_and_b32 s95, s93, 31
	s_lshl_b32 s96, s94, 4
	v_bfe_u32 v7, v3, 2, 1
	v_lshrrev_b32_e32 v6, 3, v3
	v_and_b32_e32 v10, 3, v3
	v_lshlrev_b32_e32 v7, 10, v7
	v_lshl_add_u32 v7, v6, 2, v7
	v_add_u32_e32 v7, v7, v10
	v_add_u32_e32 v7, s96, v7
	v_lshlrev_b32_e32 v7, 2, v7
	v_lshl_add_u32 v80, v4, 16, v7
	global_load_dword v84, v80, s[86:87]
	s_add_u32 s90, s86, 0x2000
	s_addc_u32 s91, s87, 0
	global_load_dword v85, v80, s[90:91]
	s_add_u32 s90, s86, 0x4000
	s_addc_u32 s91, s87, 0
	global_load_dword v86, v80, s[90:91]
	s_add_u32 s90, s86, 0x6000
	s_addc_u32 s91, s87, 0
	global_load_dword v87, v80, s[90:91]
	s_add_u32 s90, s86, 0x8000
	s_addc_u32 s91, s87, 0
	global_load_dword v88, v80, s[90:91]
	s_add_u32 s90, s86, 0xa000
	s_addc_u32 s91, s87, 0
	global_load_dword v89, v80, s[90:91]
	s_add_u32 s90, s86, 0xc000
	s_addc_u32 s91, s87, 0
	global_load_dword v90, v80, s[90:91]
	s_add_u32 s90, s86, 0xe000
	s_addc_u32 s91, s87, 0
	global_load_dword v91, v80, s[90:91]
	s_add_u32 s90, s86, 0x20000
	s_addc_u32 s91, s87, 0
	global_load_dword v92, v80, s[90:91]
	s_add_u32 s90, s86, 0x22000
	s_addc_u32 s91, s87, 0
	global_load_dword v93, v80, s[90:91]
	s_add_u32 s90, s86, 0x24000
	s_addc_u32 s91, s87, 0
	global_load_dword v94, v80, s[90:91]
	s_add_u32 s90, s86, 0x26000
	s_addc_u32 s91, s87, 0
	global_load_dword v95, v80, s[90:91]
	s_add_u32 s90, s86, 0x28000
	s_addc_u32 s91, s87, 0
	global_load_dword v96, v80, s[90:91]
	s_add_u32 s90, s86, 0x2a000
	s_addc_u32 s91, s87, 0
	global_load_dword v97, v80, s[90:91]
	s_add_u32 s90, s86, 0x2c000
	s_addc_u32 s91, s87, 0
	global_load_dword v98, v80, s[90:91]
	s_add_u32 s90, s86, 0x2e000
	s_addc_u32 s91, s87, 0
	global_load_dword v99, v80, s[90:91]
	s_add_u32 s90, s86, 0x40000
	s_addc_u32 s91, s87, 0
	global_load_dword v100, v80, s[90:91]
	s_add_u32 s90, s86, 0x42000
	s_addc_u32 s91, s87, 0
	global_load_dword v101, v80, s[90:91]
	s_add_u32 s90, s86, 0x44000
	s_addc_u32 s91, s87, 0
	global_load_dword v102, v80, s[90:91]
	s_add_u32 s90, s86, 0x46000
	s_addc_u32 s91, s87, 0
	global_load_dword v103, v80, s[90:91]
	s_add_u32 s90, s86, 0x48000
	s_addc_u32 s91, s87, 0
	global_load_dword v104, v80, s[90:91]
	s_add_u32 s90, s86, 0x4a000
	s_addc_u32 s91, s87, 0
	global_load_dword v105, v80, s[90:91]
	s_add_u32 s90, s86, 0x4c000
	s_addc_u32 s91, s87, 0
	global_load_dword v106, v80, s[90:91]
	s_add_u32 s90, s86, 0x4e000
	s_addc_u32 s91, s87, 0
	global_load_dword v107, v80, s[90:91]
	s_add_u32 s90, s86, 0x60000
	s_addc_u32 s91, s87, 0
	global_load_dword v108, v80, s[90:91]
	s_add_u32 s90, s86, 0x62000
	s_addc_u32 s91, s87, 0
	global_load_dword v109, v80, s[90:91]
	s_add_u32 s90, s86, 0x64000
	s_addc_u32 s91, s87, 0
	global_load_dword v110, v80, s[90:91]
	s_add_u32 s90, s86, 0x66000
	s_addc_u32 s91, s87, 0
	global_load_dword v111, v80, s[90:91]
	s_add_u32 s90, s86, 0x68000
	s_addc_u32 s91, s87, 0
	global_load_dword v76, v80, s[90:91]
	s_add_u32 s90, s86, 0x6a000
	s_addc_u32 s91, s87, 0
	global_load_dword v77, v80, s[90:91]
	s_add_u32 s90, s86, 0x6c000
	s_addc_u32 s91, s87, 0
	global_load_dword v78, v80, s[90:91]
	s_add_u32 s90, s86, 0x6e000
	s_addc_u32 s91, s87, 0
	global_load_dword v79, v80, s[90:91]
	s_lshl_b32 s55, s95, 14
	s_add_u32 s78, s66, 0x1a80000
	s_addc_u32 s79, s67, 0
	s_add_u32 s78, s78, s55
	s_addc_u32 s79, s79, 0
	s_add_u32 s80, s78, 0x80000
	s_addc_u32 s81, s79, 0
	global_load_dwordx4 v[112:115], v81, s[78:79]
	global_load_dwordx4 v[116:119], v81, s[78:79] offset:32
	global_load_dwordx4 v[120:123], v81, s[78:79] offset:64
	global_load_dwordx4 v[124:127], v81, s[78:79] offset:96
	global_load_dwordx4 v[128:131], v81, s[80:81]
	global_load_dwordx4 v[132:135], v81, s[80:81] offset:32
	global_load_dwordx4 v[136:139], v81, s[80:81] offset:64
	global_load_dwordx4 v[140:143], v81, s[80:81] offset:96
	s_add_u32 s78, s78, 0x1000
	s_addc_u32 s79, s79, 0
	s_add_u32 s80, s80, 0x1000
	s_addc_u32 s81, s81, 0
	global_load_dwordx4 v[144:147], v81, s[78:79]
	global_load_dwordx4 v[148:151], v81, s[78:79] offset:32
	global_load_dwordx4 v[152:155], v81, s[78:79] offset:64
	global_load_dwordx4 v[156:159], v81, s[78:79] offset:96
	global_load_dwordx4 v[160:163], v81, s[80:81]
	global_load_dwordx4 v[164:167], v81, s[80:81] offset:32
	global_load_dwordx4 v[168:171], v81, s[80:81] offset:64
	global_load_dwordx4 v[172:175], v81, s[80:81] offset:96
	s_add_u32 s78, s78, 0x1000
	s_addc_u32 s79, s79, 0
	s_add_u32 s80, s80, 0x1000
	s_addc_u32 s81, s81, 0
	global_load_dwordx4 v[176:179], v81, s[78:79]
	global_load_dwordx4 v[180:183], v81, s[78:79] offset:32
	global_load_dwordx4 v[184:187], v81, s[78:79] offset:64
	global_load_dwordx4 v[188:191], v81, s[78:79] offset:96
	global_load_dwordx4 v[192:195], v81, s[80:81]
	global_load_dwordx4 v[196:199], v81, s[80:81] offset:32
	global_load_dwordx4 v[200:203], v81, s[80:81] offset:64
	global_load_dwordx4 v[204:207], v81, s[80:81] offset:96
	s_add_u32 s78, s78, 0x1000
	s_addc_u32 s79, s79, 0
	s_add_u32 s80, s80, 0x1000
	s_addc_u32 s81, s81, 0
	global_load_dwordx4 v[208:211], v81, s[78:79]
	global_load_dwordx4 v[212:215], v81, s[78:79] offset:32
	global_load_dwordx4 v[216:219], v81, s[78:79] offset:64
	global_load_dwordx4 v[220:223], v81, s[78:79] offset:96
	global_load_dwordx4 v[224:227], v81, s[80:81]
	global_load_dwordx4 v[228:231], v81, s[80:81] offset:32
	global_load_dwordx4 v[232:235], v81, s[80:81] offset:64
	global_load_dwordx4 v[236:239], v81, s[80:81] offset:96
	s_lshl_b32 s55, s96, 14
	s_add_u32 s84, s66, 0x9c00000
	s_addc_u32 s85, s67, 0
	s_add_u32 s84, s84, s55
	s_addc_u32 s85, s85, 0
	v_and_b32_e32 v6, 15, v2
	v_add_u32_e32 v6, s96, v6
	v_cvt_f32_u32_e32 v6, v6
	v_div_scale_f32 v7, s[16:17], s61, s61, v6
	v_rcp_f32_e32 v12, v7
	v_div_scale_f32 v13, vcc, v6, s61, v6
	v_fma_f32 v10, -v7, v12, 1.0
	v_fmac_f32_e32 v12, v10, v12
	v_mul_f32_e32 v10, v13, v12
	v_fma_f32 v11, -v7, v10, v13
	v_fmac_f32_e32 v10, v11, v12
	v_fma_f32 v7, -v7, v10, v13
	s_nop 1
	v_div_fmas_f32 v7, v7, v12, v10
	v_div_fixup_f32 v6, v7, s61, v6
	v_mov_b32_e32 v7, 0xc0447cbd
	v_fmamk_f32 v6, v6, 0xc1447cbd, v7
	v_and_b32_e32 v6, 0x7fffffff, v6
	s_nop 0
	v_readlane_b32 s6, v6, 0
	v_readlane_b32 s7, v6, 1
	v_readlane_b32 s10, v6, 2
	v_readlane_b32 s11, v6, 3
	v_readlane_b32 s24, v6, 4
	v_readlane_b32 s26, v6, 5
	v_readlane_b32 s32, v6, 6
	v_readlane_b32 s35, v6, 7
	v_readlane_b32 s41, v6, 8
	v_readlane_b32 s44, v6, 9
	v_readlane_b32 s45, v6, 10
	v_readlane_b32 s47, v6, 11
	v_readlane_b32 s48, v6, 12
	v_readlane_b32 s49, v6, 13
	v_readlane_b32 s52, v6, 14
	v_readlane_b32 s53, v6, 15
	s_waitcnt vmcnt(32)
	v_cvt_pk_bf16_f32 v6, v84, v85
	v_lshlrev_b32_e32 v12, 16, v6
	v_and_b32_e32 v13, 0xffff0000, v6
	v_sub_f32_e32 v84, v84, v12
	v_sub_f32_e32 v85, v85, v13
	v_cvt_pk_bf16_f32 v70, v84, v85
	v_cvt_pk_bf16_f32 v7, v86, v87
	v_lshlrev_b32_e32 v12, 16, v7
	v_and_b32_e32 v13, 0xffff0000, v7
	v_sub_f32_e32 v86, v86, v12
	v_sub_f32_e32 v87, v87, v13
	v_cvt_pk_bf16_f32 v71, v86, v87
	v_cvt_pk_bf16_f32 v10, v88, v89
	v_lshlrev_b32_e32 v12, 16, v10
	v_and_b32_e32 v13, 0xffff0000, v10
	v_sub_f32_e32 v88, v88, v12
	v_sub_f32_e32 v89, v89, v13
	v_cvt_pk_bf16_f32 v72, v88, v89
	v_cvt_pk_bf16_f32 v11, v90, v91
	v_lshlrev_b32_e32 v12, 16, v11
	v_and_b32_e32 v13, 0xffff0000, v11
	v_sub_f32_e32 v90, v90, v12
	v_sub_f32_e32 v91, v91, v13
	v_cvt_pk_bf16_f32 v73, v90, v91
	v_mov_b32_e32 v84, v6
	v_mov_b32_e32 v88, v70
	v_mov_b32_e32 v85, v7
	v_mov_b32_e32 v89, v71
	v_mov_b32_e32 v86, v10
	v_mov_b32_e32 v90, v72
	v_mov_b32_e32 v87, v11
	v_mov_b32_e32 v91, v73
	v_cvt_pk_bf16_f32 v6, v92, v93
	v_lshlrev_b32_e32 v12, 16, v6
	v_and_b32_e32 v13, 0xffff0000, v6
	v_sub_f32_e32 v92, v92, v12
	v_sub_f32_e32 v93, v93, v13
	v_cvt_pk_bf16_f32 v70, v92, v93
	v_cvt_pk_bf16_f32 v7, v94, v95
	v_lshlrev_b32_e32 v12, 16, v7
	v_and_b32_e32 v13, 0xffff0000, v7
	v_sub_f32_e32 v94, v94, v12
	v_sub_f32_e32 v95, v95, v13
	v_cvt_pk_bf16_f32 v71, v94, v95
	v_cvt_pk_bf16_f32 v10, v96, v97
	v_lshlrev_b32_e32 v12, 16, v10
	v_and_b32_e32 v13, 0xffff0000, v10
	v_sub_f32_e32 v96, v96, v12
	v_sub_f32_e32 v97, v97, v13
	v_cvt_pk_bf16_f32 v72, v96, v97
	v_cvt_pk_bf16_f32 v11, v98, v99
	v_lshlrev_b32_e32 v12, 16, v11
	v_and_b32_e32 v13, 0xffff0000, v11
	v_sub_f32_e32 v98, v98, v12
	v_sub_f32_e32 v99, v99, v13
	v_cvt_pk_bf16_f32 v73, v98, v99
	v_mov_b32_e32 v92, v6
	v_mov_b32_e32 v96, v70
	v_mov_b32_e32 v93, v7
	v_mov_b32_e32 v97, v71
	v_mov_b32_e32 v94, v10
	v_mov_b32_e32 v98, v72
	v_mov_b32_e32 v95, v11
	v_mov_b32_e32 v99, v73
	v_cvt_pk_bf16_f32 v6, v100, v101
	v_lshlrev_b32_e32 v12, 16, v6
	v_and_b32_e32 v13, 0xffff0000, v6
	v_sub_f32_e32 v100, v100, v12
	v_sub_f32_e32 v101, v101, v13
	v_cvt_pk_bf16_f32 v70, v100, v101
	v_cvt_pk_bf16_f32 v7, v102, v103
	v_lshlrev_b32_e32 v12, 16, v7
	v_and_b32_e32 v13, 0xffff0000, v7
	v_sub_f32_e32 v102, v102, v12
	v_sub_f32_e32 v103, v103, v13
	v_cvt_pk_bf16_f32 v71, v102, v103
	v_cvt_pk_bf16_f32 v10, v104, v105
	v_lshlrev_b32_e32 v12, 16, v10
	v_and_b32_e32 v13, 0xffff0000, v10
	v_sub_f32_e32 v104, v104, v12
	v_sub_f32_e32 v105, v105, v13
	v_cvt_pk_bf16_f32 v72, v104, v105
	v_cvt_pk_bf16_f32 v11, v106, v107
	v_lshlrev_b32_e32 v12, 16, v11
	v_and_b32_e32 v13, 0xffff0000, v11
	v_sub_f32_e32 v106, v106, v12
	v_sub_f32_e32 v107, v107, v13
	v_cvt_pk_bf16_f32 v73, v106, v107
	v_mov_b32_e32 v100, v6
	v_mov_b32_e32 v104, v70
	v_mov_b32_e32 v101, v7
	v_mov_b32_e32 v105, v71
	v_mov_b32_e32 v102, v10
	v_mov_b32_e32 v106, v72
	v_mov_b32_e32 v103, v11
	v_mov_b32_e32 v107, v73
	v_cvt_pk_bf16_f32 v6, v108, v109
	v_lshlrev_b32_e32 v12, 16, v6
	v_and_b32_e32 v13, 0xffff0000, v6
	v_sub_f32_e32 v108, v108, v12
	v_sub_f32_e32 v109, v109, v13
	v_cvt_pk_bf16_f32 v70, v108, v109
	v_cvt_pk_bf16_f32 v7, v110, v111
	v_lshlrev_b32_e32 v12, 16, v7
	v_and_b32_e32 v13, 0xffff0000, v7
	v_sub_f32_e32 v110, v110, v12
	v_sub_f32_e32 v111, v111, v13
	v_cvt_pk_bf16_f32 v71, v110, v111
	v_cvt_pk_bf16_f32 v10, v76, v77
	v_lshlrev_b32_e32 v12, 16, v10
	v_and_b32_e32 v13, 0xffff0000, v10
	v_sub_f32_e32 v76, v76, v12
	v_sub_f32_e32 v77, v77, v13
	v_cvt_pk_bf16_f32 v72, v76, v77
	v_cvt_pk_bf16_f32 v11, v78, v79
	v_lshlrev_b32_e32 v12, 16, v11
	v_and_b32_e32 v13, 0xffff0000, v11
	v_sub_f32_e32 v78, v78, v12
	v_sub_f32_e32 v79, v79, v13
	v_cvt_pk_bf16_f32 v73, v78, v79
	v_mov_b32_e32 v108, v6
	v_mov_b32_e32 v76, v70
	v_mov_b32_e32 v109, v7
	v_mov_b32_e32 v77, v71
	v_mov_b32_e32 v110, v10
	v_mov_b32_e32 v78, v72
	v_mov_b32_e32 v111, v11
	v_mov_b32_e32 v79, v73
	s_lshl_b32 s55, s95, 7
	s_waitcnt vmcnt(24)
	s_nop 1
	v_mfma_f32_32x32x16_bf16 v[14:29], v[84:87], v[112:115], 0
	v_mfma_f32_32x32x16_bf16 v[14:29], v[84:87], v[128:131], v[14:29]
	v_mfma_f32_32x32x16_bf16 v[14:29], v[88:91], v[112:115], v[14:29]
	v_mfma_f32_32x32x16_bf16 v[14:29], v[92:95], v[116:119], v[14:29]
	v_mfma_f32_32x32x16_bf16 v[14:29], v[92:95], v[132:135], v[14:29]
	v_mfma_f32_32x32x16_bf16 v[14:29], v[96:99], v[116:119], v[14:29]
	v_mfma_f32_32x32x16_bf16 v[14:29], v[100:103], v[120:123], v[14:29]
	v_mfma_f32_32x32x16_bf16 v[14:29], v[100:103], v[136:139], v[14:29]
	v_mfma_f32_32x32x16_bf16 v[14:29], v[104:107], v[120:123], v[14:29]
	v_mfma_f32_32x32x16_bf16 v[14:29], v[108:111], v[124:127], v[14:29]
	v_mfma_f32_32x32x16_bf16 v[14:29], v[108:111], v[140:143], v[14:29]
	v_mfma_f32_32x32x16_bf16 v[14:29], v[76:79], v[124:127], v[14:29]
	s_waitcnt vmcnt(16)
	v_mfma_f32_32x32x16_bf16 v[32:47], v[84:87], v[144:147], 0
	v_add_u32_e32 v70, s55, v3
	v_cvt_f32_i32_e32 v71, v70
	v_mul_f32_e32 v71, 0xb9b8b5c6, v71
	v_sub_u32_e32 v72, 0x1000, v70
	v_add_u32_e32 v73, 0x1000, v70
	v_cmp_eq_u32_e32 vcc, 0, v70
	s_and_b64 s[16:17], vcc, s[14:15]
	s_andn2_b64 s[18:19], vcc, s[14:15]
	v_cndmask_b32_e64 v73, v73, 0, vcc
	v_cndmask_b32_e64 v72, v72, v73, s[14:15]
	v_lshlrev_b32_e32 v72, 1, v72
	s_mov_b64 s[90:91], s[84:85]
	s_add_i32 s55, s55, 32
	s_cmp_lg_u32 s95, 0
	s_cbranch_scc1 .Lpf_noskip
	s_lshl_b32 s72, s96, 2
	v_mfma_f32_32x32x16_bf16 v[32:47], v[84:87], v[160:163], v[32:47]
	s_add_u32 s72, s88, s72
	s_addc_u32 s73, s89, 0
	global_load_dwordx4 v[112:115], v82, s[72:73]
	global_load_dwordx4 v[116:119], v82, s[72:73] offset:16
	global_load_dwordx4 v[120:123], v82, s[72:73] offset:32
	global_load_dwordx4 v[124:127], v82, s[72:73] offset:48
	s_waitcnt vmcnt(0)
.Lpf_noskip:
	s_nop 7
	v_mul_f32_e32 v10, s6, v71
	v_mul_f32_e32 v11, s7, v71
	v_exp_f32_e32 v10, v10
	v_exp_f32_e32 v11, v11
	s_nop 0
	v_pk_add_f32 v[10:11], v[10:11], v[8:9]
	v_pk_mul_f32 v[10:11], v[10:11], v[14:15]
	v_mfma_f32_32x32x16_bf16 v[32:47], v[88:91], v[144:147], v[32:47]
	v_add_f32_e32 v6, v112, v10
	v_cndmask_b32_e64 v10, v10, v6, s[18:19]
	v_cndmask_b32_e64 v10, v10, 0, s[16:17]
	v_add_f32_e32 v6, v113, v11
	v_cndmask_b32_e64 v11, v11, v6, s[18:19]
	v_cndmask_b32_e64 v11, v11, 0, s[16:17]
	v_cvt_pk_bf16_f32 v10, v10, v11
	global_store_short v72, v10, s[90:91]
	s_add_u32 s90, s90, 0x4000
	s_addc_u32 s91, s91, 0
	global_store_short_d16_hi v72, v10, s[90:91]
	s_add_u32 s90, s90, 0x4000
	s_addc_u32 s91, s91, 0
	v_mul_f32_e32 v12, s10, v71
	v_mul_f32_e32 v13, s11, v71
	v_exp_f32_e32 v12, v12
	v_mfma_f32_32x32x16_bf16 v[32:47], v[92:95], v[148:151], v[32:47]
	v_exp_f32_e32 v13, v13
	s_nop 0
	v_pk_add_f32 v[12:13], v[12:13], v[8:9]
	v_pk_mul_f32 v[12:13], v[12:13], v[16:17]
	v_add_f32_e32 v6, v114, v12
	v_cndmask_b32_e64 v12, v12, v6, s[18:19]
	v_cndmask_b32_e64 v12, v12, 0, s[16:17]
	v_add_f32_e32 v6, v115, v13
	v_cndmask_b32_e64 v13, v13, v6, s[18:19]
	v_cndmask_b32_e64 v13, v13, 0, s[16:17]
	v_cvt_pk_bf16_f32 v12, v12, v13
	global_store_short v72, v12, s[90:91]
	s_add_u32 s90, s90, 0x4000
	s_addc_u32 s91, s91, 0
	global_store_short_d16_hi v72, v12, s[90:91]
	s_add_u32 s90, s90, 0x4000
	v_mfma_f32_32x32x16_bf16 v[32:47], v[92:95], v[164:167], v[32:47]
	s_addc_u32 s91, s91, 0
	v_mul_f32_e32 v10, s24, v71
	v_mul_f32_e32 v11, s26, v71
	v_exp_f32_e32 v10, v10
	v_exp_f32_e32 v11, v11
	s_nop 0
	v_pk_add_f32 v[10:11], v[10:11], v[8:9]
	v_pk_mul_f32 v[10:11], v[10:11], v[18:19]
	v_add_f32_e32 v6, v116, v10
	v_cndmask_b32_e64 v10, v10, v6, s[18:19]
	v_cndmask_b32_e64 v10, v10, 0, s[16:17]
	v_add_f32_e32 v6, v117, v11
	v_cndmask_b32_e64 v11, v11, v6, s[18:19]
	v_cndmask_b32_e64 v11, v11, 0, s[16:17]
	v_cvt_pk_bf16_f32 v10, v10, v11
	global_store_short v72, v10, s[90:91]
	v_mfma_f32_32x32x16_bf16 v[32:47], v[96:99], v[148:151], v[32:47]
	s_add_u32 s90, s90, 0x4000
	s_addc_u32 s91, s91, 0
	global_store_short_d16_hi v72, v10, s[90:91]
	s_add_u32 s90, s90, 0x4000
	s_addc_u32 s91, s91, 0
	v_mul_f32_e32 v12, s32, v71
	v_mul_f32_e32 v13, s35, v71
	v_exp_f32_e32 v12, v12
	v_exp_f32_e32 v13, v13
	s_nop 0
	v_pk_add_f32 v[12:13], v[12:13], v[8:9]
	v_pk_mul_f32 v[12:13], v[12:13], v[20:21]
	v_add_f32_e32 v6, v118, v12
	v_cndmask_b32_e64 v12, v12, v6, s[18:19]
	v_cndmask_b32_e64 v12, v12, 0, s[16:17]
	v_add_f32_e32 v6, v119, v13
	v_mfma_f32_32x32x16_bf16 v[32:47], v[100:103], v[152:155], v[32:47]
	v_cndmask_b32_e64 v13, v13, v6, s[18:19]
	v_cndmask_b32_e64 v13, v13, 0, s[16:17]
	v_cvt_pk_bf16_f32 v12, v12, v13
	global_store_short v72, v12, s[90:91]
	s_add_u32 s90, s90, 0x4000
	s_addc_u32 s91, s91, 0
	global_store_short_d16_hi v72, v12, s[90:91]
	s_add_u32 s90, s90, 0x4000
	s_addc_u32 s91, s91, 0
	v_mul_f32_e32 v10, s41, v71
	v_mul_f32_e32 v11, s44, v71
	v_exp_f32_e32 v10, v10
	v_exp_f32_e32 v11, v11
	s_nop 0
	v_pk_add_f32 v[10:11], v[10:11], v[8:9]
	v_pk_mul_f32 v[10:11], v[10:11], v[22:23]
	v_mfma_f32_32x32x16_bf16 v[32:47], v[100:103], v[168:171], v[32:47]
	v_add_f32_e32 v6, v120, v10
	v_cndmask_b32_e64 v10, v10, v6, s[18:19]
	v_cndmask_b32_e64 v10, v10, 0, s[16:17]
	v_add_f32_e32 v6, v121, v11
	v_cndmask_b32_e64 v11, v11, v6, s[18:19]
	v_cndmask_b32_e64 v11, v11, 0, s[16:17]
	v_cvt_pk_bf16_f32 v10, v10, v11
	global_store_short v72, v10, s[90:91]
	s_add_u32 s90, s90, 0x4000
	s_addc_u32 s91, s91, 0
	global_store_short_d16_hi v72, v10, s[90:91]
	s_add_u32 s90, s90, 0x4000
	s_addc_u32 s91, s91, 0
	v_mul_f32_e32 v12, s45, v71
	v_mul_f32_e32 v13, s47, v71
	v_exp_f32_e32 v12, v12
	v_mfma_f32_32x32x16_bf16 v[32:47], v[104:107], v[152:155], v[32:47]
	v_exp_f32_e32 v13, v13
	s_nop 0
	v_pk_add_f32 v[12:13], v[12:13], v[8:9]
	v_pk_mul_f32 v[12:13], v[12:13], v[24:25]
	v_add_f32_e32 v6, v122, v12
	v_cndmask_b32_e64 v12, v12, v6, s[18:19]
	v_cndmask_b32_e64 v12, v12, 0, s[16:17]
	v_add_f32_e32 v6, v123, v13
	v_cndmask_b32_e64 v13, v13, v6, s[18:19]
	v_cndmask_b32_e64 v13, v13, 0, s[16:17]
	v_cvt_pk_bf16_f32 v12, v12, v13
	global_store_short v72, v12, s[90:91]
	s_add_u32 s90, s90, 0x4000
	s_addc_u32 s91, s91, 0
	global_store_short_d16_hi v72, v12, s[90:91]
	s_add_u32 s90, s90, 0x4000
	v_mfma_f32_32x32x16_bf16 v[32:47], v[108:111], v[156:159], v[32:47]
	s_addc_u32 s91, s91, 0
	v_mul_f32_e32 v10, s48, v71
	v_mul_f32_e32 v11, s49, v71
	v_exp_f32_e32 v10, v10
	v_exp_f32_e32 v11, v11
	s_nop 0
	v_pk_add_f32 v[10:11], v[10:11], v[8:9]
	v_pk_mul_f32 v[10:11], v[10:11], v[26:27]
	v_add_f32_e32 v6, v124, v10
	v_cndmask_b32_e64 v10, v10, v6, s[18:19]
	v_cndmask_b32_e64 v10, v10, 0, s[16:17]
	v_add_f32_e32 v6, v125, v11
	v_cndmask_b32_e64 v11, v11, v6, s[18:19]
	v_cndmask_b32_e64 v11, v11, 0, s[16:17]
	v_cvt_pk_bf16_f32 v10, v10, v11
	global_store_short v72, v10, s[90:91]
	v_mfma_f32_32x32x16_bf16 v[32:47], v[108:111], v[172:175], v[32:47]
	s_add_u32 s90, s90, 0x4000
	s_addc_u32 s91, s91, 0
	global_store_short_d16_hi v72, v10, s[90:91]
	s_add_u32 s90, s90, 0x4000
	s_addc_u32 s91, s91, 0
	v_mul_f32_e32 v12, s52, v71
	v_mul_f32_e32 v13, s53, v71
	v_exp_f32_e32 v12, v12
	v_exp_f32_e32 v13, v13
	s_nop 0
	v_pk_add_f32 v[12:13], v[12:13], v[8:9]
	v_pk_mul_f32 v[12:13], v[12:13], v[28:29]
	v_add_f32_e32 v6, v126, v12
	v_cndmask_b32_e64 v12, v12, v6, s[18:19]
	v_cndmask_b32_e64 v12, v12, 0, s[16:17]
	v_add_f32_e32 v6, v127, v13
	v_mfma_f32_32x32x16_bf16 v[32:47], v[76:79], v[156:159], v[32:47]
	v_cndmask_b32_e64 v13, v13, v6, s[18:19]
	v_cndmask_b32_e64 v13, v13, 0, s[16:17]
	v_cvt_pk_bf16_f32 v12, v12, v13
	global_store_short v72, v12, s[90:91]
	s_add_u32 s90, s90, 0x4000
	s_addc_u32 s91, s91, 0
	global_store_short_d16_hi v72, v12, s[90:91]
	s_waitcnt vmcnt(24)
	v_mfma_f32_32x32x16_bf16 v[14:29], v[84:87], v[176:179], 0
	v_add_u32_e32 v70, s55, v3
	v_cvt_f32_i32_e32 v71, v70
	v_mul_f32_e32 v71, 0xb9b8b5c6, v71
	v_sub_u32_e32 v72, 0x1000, v70
	v_add_u32_e32 v73, 0x1000, v70
	v_cndmask_b32_e64 v72, v72, v73, s[14:15]
	v_lshlrev_b32_e32 v72, 1, v72
	s_mov_b64 s[90:91], s[84:85]
	s_add_i32 s55, s55, 32
	s_nop 7
	v_mfma_f32_32x32x16_bf16 v[14:29], v[84:87], v[192:195], v[14:29]
	v_mul_f32_e32 v10, s6, v71
	v_mul_f32_e32 v11, s7, v71
	v_exp_f32_e32 v10, v10
	v_exp_f32_e32 v11, v11
	s_nop 0
	v_pk_add_f32 v[10:11], v[10:11], v[8:9]
	v_pk_mul_f32 v[10:11], v[10:11], v[32:33]
	v_cvt_pk_bf16_f32 v10, v10, v11
	global_store_short v72, v10, s[90:91]
	s_add_u32 s90, s90, 0x4000
	v_mfma_f32_32x32x16_bf16 v[14:29], v[88:91], v[176:179], v[14:29]
	s_addc_u32 s91, s91, 0
	global_store_short_d16_hi v72, v10, s[90:91]
	s_add_u32 s90, s90, 0x4000
	s_addc_u32 s91, s91, 0
	v_mul_f32_e32 v12, s10, v71
	v_mul_f32_e32 v13, s11, v71
	v_exp_f32_e32 v12, v12
	v_exp_f32_e32 v13, v13
	s_nop 0
	v_pk_add_f32 v[12:13], v[12:13], v[8:9]
	v_mfma_f32_32x32x16_bf16 v[14:29], v[92:95], v[180:183], v[14:29]
	v_pk_mul_f32 v[12:13], v[12:13], v[34:35]
	v_cvt_pk_bf16_f32 v12, v12, v13
	global_store_short v72, v12, s[90:91]
	s_add_u32 s90, s90, 0x4000
	s_addc_u32 s91, s91, 0
	global_store_short_d16_hi v72, v12, s[90:91]
	s_add_u32 s90, s90, 0x4000
	s_addc_u32 s91, s91, 0
	v_mul_f32_e32 v10, s24, v71
	v_mul_f32_e32 v11, s26, v71
	v_mfma_f32_32x32x16_bf16 v[14:29], v[92:95], v[196:199], v[14:29]
	v_exp_f32_e32 v10, v10
	v_exp_f32_e32 v11, v11
	s_nop 0
	v_pk_add_f32 v[10:11], v[10:11], v[8:9]
	v_pk_mul_f32 v[10:11], v[10:11], v[36:37]
	v_cvt_pk_bf16_f32 v10, v10, v11
	global_store_short v72, v10, s[90:91]
	s_add_u32 s90, s90, 0x4000
	s_addc_u32 s91, s91, 0
	global_store_short_d16_hi v72, v10, s[90:91]
	v_mfma_f32_32x32x16_bf16 v[14:29], v[96:99], v[180:183], v[14:29]
	s_add_u32 s90, s90, 0x4000
	s_addc_u32 s91, s91, 0
	v_mul_f32_e32 v12, s32, v71
	v_mul_f32_e32 v13, s35, v71
	v_exp_f32_e32 v12, v12
	v_exp_f32_e32 v13, v13
	s_nop 0
	v_pk_add_f32 v[12:13], v[12:13], v[8:9]
	v_pk_mul_f32 v[12:13], v[12:13], v[38:39]
	v_cvt_pk_bf16_f32 v12, v12, v13
	v_mfma_f32_32x32x16_bf16 v[14:29], v[100:103], v[184:187], v[14:29]
	global_store_short v72, v12, s[90:91]
	s_add_u32 s90, s90, 0x4000
	s_addc_u32 s91, s91, 0
	global_store_short_d16_hi v72, v12, s[90:91]
	s_add_u32 s90, s90, 0x4000
	s_addc_u32 s91, s91, 0
	v_mul_f32_e32 v10, s41, v71
	v_mul_f32_e32 v11, s44, v71
	v_exp_f32_e32 v10, v10
	v_exp_f32_e32 v11, v11
	v_mfma_f32_32x32x16_bf16 v[14:29], v[100:103], v[200:203], v[14:29]
	s_nop 0
	v_pk_add_f32 v[10:11], v[10:11], v[8:9]
	v_pk_mul_f32 v[10:11], v[10:11], v[40:41]
	v_cvt_pk_bf16_f32 v10, v10, v11
	global_store_short v72, v10, s[90:91]
	s_add_u32 s90, s90, 0x4000
	s_addc_u32 s91, s91, 0
	global_store_short_d16_hi v72, v10, s[90:91]
	s_add_u32 s90, s90, 0x4000
	s_addc_u32 s91, s91, 0
	v_mfma_f32_32x32x16_bf16 v[14:29], v[104:107], v[184:187], v[14:29]
	v_mul_f32_e32 v12, s45, v71
	v_mul_f32_e32 v13, s47, v71
	v_exp_f32_e32 v12, v12
	v_exp_f32_e32 v13, v13
	s_nop 0
	v_pk_add_f32 v[12:13], v[12:13], v[8:9]
	v_pk_mul_f32 v[12:13], v[12:13], v[42:43]
	v_cvt_pk_bf16_f32 v12, v12, v13
	global_store_short v72, v12, s[90:91]
	s_add_u32 s90, s90, 0x4000
	v_mfma_f32_32x32x16_bf16 v[14:29], v[108:111], v[188:191], v[14:29]
	s_addc_u32 s91, s91, 0
	global_store_short_d16_hi v72, v12, s[90:91]
	s_add_u32 s90, s90, 0x4000
	s_addc_u32 s91, s91, 0
	v_mul_f32_e32 v10, s48, v71
	v_mul_f32_e32 v11, s49, v71
	v_exp_f32_e32 v10, v10
	v_exp_f32_e32 v11, v11
	s_nop 0
	v_pk_add_f32 v[10:11], v[10:11], v[8:9]
	v_mfma_f32_32x32x16_bf16 v[14:29], v[108:111], v[204:207], v[14:29]
	v_pk_mul_f32 v[10:11], v[10:11], v[44:45]
	v_cvt_pk_bf16_f32 v10, v10, v11
	global_store_short v72, v10, s[90:91]
	s_add_u32 s90, s90, 0x4000
	s_addc_u32 s91, s91, 0
	global_store_short_d16_hi v72, v10, s[90:91]
	s_add_u32 s90, s90, 0x4000
	s_addc_u32 s91, s91, 0
	v_mul_f32_e32 v12, s52, v71
	v_mul_f32_e32 v13, s53, v71
	v_mfma_f32_32x32x16_bf16 v[14:29], v[76:79], v[188:191], v[14:29]
	v_exp_f32_e32 v12, v12
	v_exp_f32_e32 v13, v13
	s_nop 0
	v_pk_add_f32 v[12:13], v[12:13], v[8:9]
	v_pk_mul_f32 v[12:13], v[12:13], v[46:47]
	v_cvt_pk_bf16_f32 v12, v12, v13
	global_store_short v72, v12, s[90:91]
	s_add_u32 s90, s90, 0x4000
	s_addc_u32 s91, s91, 0
	global_store_short_d16_hi v72, v12, s[90:91]
	s_waitcnt vmcnt(32)
	v_mfma_f32_32x32x16_bf16 v[32:47], v[84:87], v[208:211], 0
	v_add_u32_e32 v70, s55, v3
	v_cvt_f32_i32_e32 v71, v70
	v_mul_f32_e32 v71, 0xb9b8b5c6, v71
	v_sub_u32_e32 v72, 0x1000, v70
	v_add_u32_e32 v73, 0x1000, v70
	v_cndmask_b32_e64 v72, v72, v73, s[14:15]
	v_lshlrev_b32_e32 v72, 1, v72
	s_mov_b64 s[90:91], s[84:85]
	s_add_i32 s55, s55, 32
	s_nop 7
	v_mfma_f32_32x32x16_bf16 v[32:47], v[84:87], v[224:227], v[32:47]
	v_mul_f32_e32 v10, s6, v71
	v_mul_f32_e32 v11, s7, v71
	v_exp_f32_e32 v10, v10
	v_exp_f32_e32 v11, v11
	s_nop 0
	v_pk_add_f32 v[10:11], v[10:11], v[8:9]
	v_pk_mul_f32 v[10:11], v[10:11], v[14:15]
	v_cvt_pk_bf16_f32 v10, v10, v11
	global_store_short v72, v10, s[90:91]
	s_add_u32 s90, s90, 0x4000
	v_mfma_f32_32x32x16_bf16 v[32:47], v[88:91], v[208:211], v[32:47]
	s_addc_u32 s91, s91, 0
	global_store_short_d16_hi v72, v10, s[90:91]
	s_add_u32 s90, s90, 0x4000
	s_addc_u32 s91, s91, 0
	v_mul_f32_e32 v12, s10, v71
	v_mul_f32_e32 v13, s11, v71
	v_exp_f32_e32 v12, v12
	v_exp_f32_e32 v13, v13
	s_nop 0
	v_pk_add_f32 v[12:13], v[12:13], v[8:9]
	v_mfma_f32_32x32x16_bf16 v[32:47], v[92:95], v[212:215], v[32:47]
	v_pk_mul_f32 v[12:13], v[12:13], v[16:17]
	v_cvt_pk_bf16_f32 v12, v12, v13
	global_store_short v72, v12, s[90:91]
	s_add_u32 s90, s90, 0x4000
	s_addc_u32 s91, s91, 0
	global_store_short_d16_hi v72, v12, s[90:91]
	s_add_u32 s90, s90, 0x4000
	s_addc_u32 s91, s91, 0
	v_mul_f32_e32 v10, s24, v71
	v_mul_f32_e32 v11, s26, v71
	v_mfma_f32_32x32x16_bf16 v[32:47], v[92:95], v[228:231], v[32:47]
	v_exp_f32_e32 v10, v10
	v_exp_f32_e32 v11, v11
	s_nop 0
	v_pk_add_f32 v[10:11], v[10:11], v[8:9]
	v_pk_mul_f32 v[10:11], v[10:11], v[18:19]
	v_cvt_pk_bf16_f32 v10, v10, v11
	global_store_short v72, v10, s[90:91]
	s_add_u32 s90, s90, 0x4000
	s_addc_u32 s91, s91, 0
	global_store_short_d16_hi v72, v10, s[90:91]
	v_mfma_f32_32x32x16_bf16 v[32:47], v[96:99], v[212:215], v[32:47]
	s_add_u32 s90, s90, 0x4000
	s_addc_u32 s91, s91, 0
	v_mul_f32_e32 v12, s32, v71
	v_mul_f32_e32 v13, s35, v71
	v_exp_f32_e32 v12, v12
	v_exp_f32_e32 v13, v13
	s_nop 0
	v_pk_add_f32 v[12:13], v[12:13], v[8:9]
	v_pk_mul_f32 v[12:13], v[12:13], v[20:21]
	v_cvt_pk_bf16_f32 v12, v12, v13
	v_mfma_f32_32x32x16_bf16 v[32:47], v[100:103], v[216:219], v[32:47]
	global_store_short v72, v12, s[90:91]
	s_add_u32 s90, s90, 0x4000
	s_addc_u32 s91, s91, 0
	global_store_short_d16_hi v72, v12, s[90:91]
	s_add_u32 s90, s90, 0x4000
	s_addc_u32 s91, s91, 0
	v_mul_f32_e32 v10, s41, v71
	v_mul_f32_e32 v11, s44, v71
	v_exp_f32_e32 v10, v10
	v_exp_f32_e32 v11, v11
	v_mfma_f32_32x32x16_bf16 v[32:47], v[100:103], v[232:235], v[32:47]
	s_nop 0
	v_pk_add_f32 v[10:11], v[10:11], v[8:9]
	v_pk_mul_f32 v[10:11], v[10:11], v[22:23]
	v_cvt_pk_bf16_f32 v10, v10, v11
	global_store_short v72, v10, s[90:91]
	s_add_u32 s90, s90, 0x4000
	s_addc_u32 s91, s91, 0
	global_store_short_d16_hi v72, v10, s[90:91]
	s_add_u32 s90, s90, 0x4000
	s_addc_u32 s91, s91, 0
	v_mfma_f32_32x32x16_bf16 v[32:47], v[104:107], v[216:219], v[32:47]
	v_mul_f32_e32 v12, s45, v71
	v_mul_f32_e32 v13, s47, v71
	v_exp_f32_e32 v12, v12
	v_exp_f32_e32 v13, v13
	s_nop 0
	v_pk_add_f32 v[12:13], v[12:13], v[8:9]
	v_pk_mul_f32 v[12:13], v[12:13], v[24:25]
	v_cvt_pk_bf16_f32 v12, v12, v13
	global_store_short v72, v12, s[90:91]
	s_add_u32 s90, s90, 0x4000
	v_mfma_f32_32x32x16_bf16 v[32:47], v[108:111], v[220:223], v[32:47]
	s_addc_u32 s91, s91, 0
	global_store_short_d16_hi v72, v12, s[90:91]
	s_add_u32 s90, s90, 0x4000
	s_addc_u32 s91, s91, 0
	v_mul_f32_e32 v10, s48, v71
	v_mul_f32_e32 v11, s49, v71
	v_exp_f32_e32 v10, v10
	v_exp_f32_e32 v11, v11
	s_nop 0
	v_pk_add_f32 v[10:11], v[10:11], v[8:9]
	v_mfma_f32_32x32x16_bf16 v[32:47], v[108:111], v[236:239], v[32:47]
	v_pk_mul_f32 v[10:11], v[10:11], v[26:27]
	v_cvt_pk_bf16_f32 v10, v10, v11
	global_store_short v72, v10, s[90:91]
	s_add_u32 s90, s90, 0x4000
	s_addc_u32 s91, s91, 0
	global_store_short_d16_hi v72, v10, s[90:91]
	s_add_u32 s90, s90, 0x4000
	s_addc_u32 s91, s91, 0
	v_mul_f32_e32 v12, s52, v71
	v_mul_f32_e32 v13, s53, v71
	v_mfma_f32_32x32x16_bf16 v[32:47], v[76:79], v[220:223], v[32:47]
	v_exp_f32_e32 v12, v12
	v_exp_f32_e32 v13, v13
	s_nop 0
	v_pk_add_f32 v[12:13], v[12:13], v[8:9]
	v_pk_mul_f32 v[12:13], v[12:13], v[28:29]
	v_cvt_pk_bf16_f32 v12, v12, v13
	global_store_short v72, v12, s[90:91]
	s_add_u32 s90, s90, 0x4000
	s_addc_u32 s91, s91, 0
	global_store_short_d16_hi v72, v12, s[90:91]
	s_nop 7
	v_add_u32_e32 v70, s55, v3
	v_cvt_f32_i32_e32 v71, v70
	v_mul_f32_e32 v71, 0xb9b8b5c6, v71
	v_sub_u32_e32 v72, 0x1000, v70
	v_add_u32_e32 v73, 0x1000, v70
	v_cndmask_b32_e64 v72, v72, v73, s[14:15]
	v_lshlrev_b32_e32 v72, 1, v72
	s_mov_b64 s[90:91], s[84:85]
	s_nop 7
	v_mul_f32_e32 v10, s6, v71
	v_mul_f32_e32 v11, s7, v71
	v_exp_f32_e32 v10, v10
	v_exp_f32_e32 v11, v11
	s_nop 0
	v_pk_add_f32 v[10:11], v[10:11], v[8:9]
	v_pk_mul_f32 v[10:11], v[10:11], v[32:33]
	v_cvt_pk_bf16_f32 v10, v10, v11
	global_store_short v72, v10, s[90:91]
	s_add_u32 s90, s90, 0x4000
	s_addc_u32 s91, s91, 0
	global_store_short_d16_hi v72, v10, s[90:91]
	s_add_u32 s90, s90, 0x4000
	s_addc_u32 s91, s91, 0
	v_mul_f32_e32 v12, s10, v71
	v_mul_f32_e32 v13, s11, v71
	v_exp_f32_e32 v12, v12
	v_exp_f32_e32 v13, v13
	s_nop 0
	v_pk_add_f32 v[12:13], v[12:13], v[8:9]
	v_pk_mul_f32 v[12:13], v[12:13], v[34:35]
	v_cvt_pk_bf16_f32 v12, v12, v13
	global_store_short v72, v12, s[90:91]
	s_add_u32 s90, s90, 0x4000
	s_addc_u32 s91, s91, 0
	global_store_short_d16_hi v72, v12, s[90:91]
	s_add_u32 s90, s90, 0x4000
	s_addc_u32 s91, s91, 0
	v_mul_f32_e32 v10, s24, v71
	v_mul_f32_e32 v11, s26, v71
	v_exp_f32_e32 v10, v10
	v_exp_f32_e32 v11, v11
	s_nop 0
	v_pk_add_f32 v[10:11], v[10:11], v[8:9]
	v_pk_mul_f32 v[10:11], v[10:11], v[36:37]
	v_cvt_pk_bf16_f32 v10, v10, v11
	global_store_short v72, v10, s[90:91]
	s_add_u32 s90, s90, 0x4000
	s_addc_u32 s91, s91, 0
	global_store_short_d16_hi v72, v10, s[90:91]
	s_add_u32 s90, s90, 0x4000
	s_addc_u32 s91, s91, 0
	v_mul_f32_e32 v12, s32, v71
	v_mul_f32_e32 v13, s35, v71
	v_exp_f32_e32 v12, v12
	v_exp_f32_e32 v13, v13
	s_nop 0
	v_pk_add_f32 v[12:13], v[12:13], v[8:9]
	v_pk_mul_f32 v[12:13], v[12:13], v[38:39]
	v_cvt_pk_bf16_f32 v12, v12, v13
	global_store_short v72, v12, s[90:91]
	s_add_u32 s90, s90, 0x4000
	s_addc_u32 s91, s91, 0
	global_store_short_d16_hi v72, v12, s[90:91]
	s_add_u32 s90, s90, 0x4000
	s_addc_u32 s91, s91, 0
	v_mul_f32_e32 v10, s41, v71
	v_mul_f32_e32 v11, s44, v71
	v_exp_f32_e32 v10, v10
	v_exp_f32_e32 v11, v11
	s_nop 0
	v_pk_add_f32 v[10:11], v[10:11], v[8:9]
	v_pk_mul_f32 v[10:11], v[10:11], v[40:41]
	v_cvt_pk_bf16_f32 v10, v10, v11
	global_store_short v72, v10, s[90:91]
	s_add_u32 s90, s90, 0x4000
	s_addc_u32 s91, s91, 0
	global_store_short_d16_hi v72, v10, s[90:91]
	s_add_u32 s90, s90, 0x4000
	s_addc_u32 s91, s91, 0
	v_mul_f32_e32 v12, s45, v71
	v_mul_f32_e32 v13, s47, v71
	v_exp_f32_e32 v12, v12
	v_exp_f32_e32 v13, v13
	s_nop 0
	v_pk_add_f32 v[12:13], v[12:13], v[8:9]
	v_pk_mul_f32 v[12:13], v[12:13], v[42:43]
	v_cvt_pk_bf16_f32 v12, v12, v13
	global_store_short v72, v12, s[90:91]
	s_add_u32 s90, s90, 0x4000
	s_addc_u32 s91, s91, 0
	global_store_short_d16_hi v72, v12, s[90:91]
	s_add_u32 s90, s90, 0x4000
	s_addc_u32 s91, s91, 0
	v_mul_f32_e32 v10, s48, v71
	v_mul_f32_e32 v11, s49, v71
	v_exp_f32_e32 v10, v10
	v_exp_f32_e32 v11, v11
	s_nop 0
	v_pk_add_f32 v[10:11], v[10:11], v[8:9]
	v_pk_mul_f32 v[10:11], v[10:11], v[44:45]
	v_cvt_pk_bf16_f32 v10, v10, v11
	global_store_short v72, v10, s[90:91]
	s_add_u32 s90, s90, 0x4000
	s_addc_u32 s91, s91, 0
	global_store_short_d16_hi v72, v10, s[90:91]
	s_add_u32 s90, s90, 0x4000
	s_addc_u32 s91, s91, 0
	v_mul_f32_e32 v12, s52, v71
	v_mul_f32_e32 v13, s53, v71
	v_exp_f32_e32 v12, v12
	v_exp_f32_e32 v13, v13
	s_nop 0
	v_pk_add_f32 v[12:13], v[12:13], v[8:9]
	v_pk_mul_f32 v[12:13], v[12:13], v[46:47]
	v_cvt_pk_bf16_f32 v12, v12, v13
	global_store_short v72, v12, s[90:91]
	s_add_u32 s90, s90, 0x4000
	s_addc_u32 s91, s91, 0
	global_store_short_d16_hi v72, v12, s[90:91]
	s_add_i32 s93, s93, s70
	s_branch .Lpf_item
